# A-half row-sum adds moved ahead of the barrier (behind the LDS tile writes); rare-path temps renamed to free VGPRs
# baseline (speedup 1.0000x reference)
.LBB0_893:
	v_max_f32_e32 v248, v246, v75
	v_max_f32_e32 v249, v247, v67
	v_max_f32_e32 v250, v248, v249
	v_cmp_lt_f32_e32 vcc, s8, v250
	s_cbranch_vccz .LBB0_895
	v_and_b32_e32 v251, 64, v202
	v_xor_b32_e32 v250, 16, v202
	v_add_u32_e32 v251, 64, v251
	v_cmp_lt_i32_e32 vcc, v250, v251
	v_xor_b32_e32 v253, 32, v202
	s_nop 0
	v_cndmask_b32_e32 v250, v202, v250, vcc
	v_lshlrev_b32_e32 v250, 2, v250
	ds_bpermute_b32 v252, v250, v249
	ds_bpermute_b32 v250, v250, v248
	v_cmp_lt_i32_e32 vcc, v253, v251
	v_max_f32_e32 v249, v249, v249
	v_max_f32_e32 v248, v248, v248
	s_waitcnt lgkmcnt(1)
	v_max_f32_e32 v252, v252, v252
	v_cndmask_b32_e32 v251, v202, v253, vcc
	v_max_f32_e32 v249, v249, v252
	v_lshlrev_b32_e32 v251, 2, v251
	s_waitcnt lgkmcnt(0)
	v_max_f32_e32 v250, v250, v250
	ds_bpermute_b32 v252, v251, v249
	v_max_f32_e32 v248, v248, v250
	ds_bpermute_b32 v250, v251, v248
	s_waitcnt lgkmcnt(1)
	v_max_f32_e32 v251, v252, v252
	v_max_f32_e32 v249, v249, v251
	s_waitcnt lgkmcnt(0)
	v_max_f32_e32 v250, v250, v250
	v_max_f32_e32 v248, v248, v250
	v_cmp_lt_f32_e32 vcc, s8, v249
	s_nop 1
	v_cndmask_b32_e32 v249, 0, v249, vcc
	v_cmp_lt_f32_e32 vcc, s8, v248
	v_sub_f32_e32 v84, v84, v249
	v_sub_f32_e32 v85, v85, v249
	v_cndmask_b32_e32 v252, 0, v248, vcc
	v_exp_f32_e64 v248, -v249
	v_exp_f32_e64 v250, -v252
	v_sub_f32_e32 v86, v86, v249
	v_sub_f32_e32 v87, v87, v249
	v_sub_f32_e32 v88, v88, v252
	v_pk_mul_f32 v[106:107], v[106:107], v[250:251] op_sel_hi:[1,0]
	v_pk_mul_f32 v[104:105], v[104:105], v[250:251] op_sel_hi:[1,0]
	v_pk_mul_f32 v[102:103], v[102:103], v[250:251] op_sel_hi:[1,0]
	v_pk_mul_f32 v[100:101], v[100:101], v[250:251] op_sel_hi:[1,0]
	v_pk_mul_f32 v[98:99], v[98:99], v[250:251] op_sel_hi:[1,0]
	v_pk_mul_f32 v[96:97], v[96:97], v[250:251] op_sel_hi:[1,0]
	v_pk_mul_f32 v[94:95], v[94:95], v[250:251] op_sel_hi:[1,0]
	v_pk_mul_f32 v[92:93], v[92:93], v[250:251] op_sel_hi:[1,0]
	v_mov_b32_e32 v251, v248
	v_sub_f32_e32 v89, v89, v252
	v_sub_f32_e32 v90, v90, v252
	v_sub_f32_e32 v91, v91, v252
	v_pk_mul_f32 v[122:123], v[122:123], v[248:249] op_sel_hi:[1,0]
	v_pk_mul_f32 v[120:121], v[120:121], v[248:249] op_sel_hi:[1,0]
	v_sub_f32_e32 v76, v76, v249
	v_sub_f32_e32 v77, v77, v249
	v_sub_f32_e32 v78, v78, v249
	v_sub_f32_e32 v79, v79, v249
	v_sub_f32_e32 v80, v80, v252
	v_sub_f32_e32 v81, v81, v252
	v_sub_f32_e32 v82, v82, v252
	v_sub_f32_e32 v83, v83, v252
	v_pk_mul_f32 v[118:119], v[118:119], v[248:249] op_sel_hi:[1,0]
	v_pk_mul_f32 v[116:117], v[116:117], v[248:249] op_sel_hi:[1,0]
	v_sub_f32_e32 v60, v60, v249
	v_sub_f32_e32 v61, v61, v249
	v_sub_f32_e32 v62, v62, v249
	v_sub_f32_e32 v63, v63, v249
	v_sub_f32_e32 v68, v68, v252
	v_sub_f32_e32 v69, v69, v252
	v_sub_f32_e32 v70, v70, v252
	v_sub_f32_e32 v71, v71, v252
	v_pk_mul_f32 v[114:115], v[114:115], v[248:249] op_sel_hi:[1,0]
	v_pk_mul_f32 v[112:113], v[112:113], v[248:249] op_sel_hi:[1,0]
	v_sub_f32_e32 v64, v64, v249
	v_sub_f32_e32 v65, v65, v249
	v_sub_f32_e32 v66, v66, v249
	v_sub_f32_e32 v67, v67, v249
	v_sub_f32_e32 v72, v72, v252
	v_sub_f32_e32 v73, v73, v252
	v_sub_f32_e32 v74, v74, v252
	v_sub_f32_e32 v75, v75, v252
	v_pk_mul_f32 v[110:111], v[110:111], v[248:249] op_sel_hi:[1,0]
	v_pk_mul_f32 v[108:109], v[108:109], v[248:249] op_sel_hi:[1,0]
	v_pk_mul_f32 v[184:185], v[184:185], v[250:251]
	v_sub_f32_e32 v47, v47, v249
	v_sub_f32_e32 v46, v46, v249
	v_sub_f32_e32 v45, v45, v249
	v_sub_f32_e32 v44, v44, v249
	v_sub_f32_e32 v51, v51, v252
	v_sub_f32_e32 v50, v50, v252
	v_sub_f32_e32 v49, v49, v252
	v_sub_f32_e32 v48, v48, v252

.LBB0_899:
	s_cmpk_gt_u32 s26, 0x7b
	s_waitcnt vmcnt(0)
	ds_write2_b64 v1, v[56:57], v[58:59] offset1:32
	v_pk_add_f32 v[236:237], v[194:195], v[86:87]
	v_pk_add_f32 v[238:239], v[192:193], v[84:85]
	v_pk_add_f32 v[240:241], v[80:81], v[190:191]
	v_pk_add_f32 v[242:243], v[78:79], v[88:89]
	v_pk_add_f32 v[236:237], v[236:237], v[76:77]
	v_pk_add_f32 v[238:239], v[60:61], v[238:239]
	v_pk_add_f32 v[240:241], v[68:69], v[240:241]
	v_pk_add_f32 v[242:243], v[62:63], v[242:243]
	v_pk_add_f32 v[236:237], v[236:237], v[82:83]
	v_pk_add_f32 v[238:239], v[70:71], v[238:239]
	v_pk_add_f32 v[240:241], v[64:65], v[240:241]
	v_pk_add_f32 v[242:243], v[66:67], v[242:243]
	v_pk_add_f32 v[238:239], v[236:237], v[238:239]
	v_pk_add_f32 v[242:243], v[240:241], v[242:243]
	s_nop 0
	v_pk_add_f32 v[238:239], v[238:239], v[242:243]
	s_nop 0
	v_pk_add_f32 v[184:185], v[184:185], v[238:239]
	s_waitcnt lgkmcnt(0)
	s_barrier
	s_cbranch_scc1 .LBB0_903
	v_add_co_u32_e32 v52, vcc, 0x2cd20000, v186
	s_nop 1
	v_addc_co_u32_e32 v53, vcc, 0, v187, vcc
	global_load_dwordx4 v[52:55], v[52:53], off
	s_and_saveexec_b64 s[16:17], s[10:11]
	s_cbranch_execz .LBB0_902
	global_load_dwordx4 v[28:31], v[180:181], off

.LBB0_903:
	v_cndmask_b32_e64 v203, 0, 1, s[50:51]
	v_cmp_ne_u32_e64 s[16:17], 1, v203
	s_andn2_b64 vcc, exec, s[50:51]
	s_cbranch_vccnz .LBB0_905
	v_add_co_u32_e32 v56, vcc, 0x338c0000, v188
	s_nop 1
	v_addc_co_u32_e32 v57, vcc, 0, v189, vcc
	global_load_dwordx4 v[56:59], v[56:57], off offset:640
.LBB0_905:
	v_max_f32_e32 v248, v244, v131
	v_max_f32_e32 v249, v245, v127
	v_max_f32_e32 v250, v249, v248
	v_cmp_lt_f32_e32 vcc, s8, v250
	s_cbranch_vccz .LBB0_907
	v_and_b32_e32 v251, 64, v202
	v_xor_b32_e32 v250, 16, v202
	v_add_u32_e32 v251, 64, v251
	v_cmp_lt_i32_e32 vcc, v250, v251
	v_xor_b32_e32 v253, 32, v202
	s_nop 0
	v_cndmask_b32_e32 v250, v202, v250, vcc
	v_lshlrev_b32_e32 v250, 2, v250
	ds_bpermute_b32 v252, v250, v249
	ds_bpermute_b32 v250, v250, v248
	v_cmp_lt_i32_e32 vcc, v253, v251
	v_max_f32_e32 v249, v249, v249
	v_max_f32_e32 v248, v248, v248
	s_waitcnt lgkmcnt(1)
	v_max_f32_e32 v252, v252, v252
	v_cndmask_b32_e32 v251, v202, v253, vcc
	v_max_f32_e32 v249, v249, v252
	v_lshlrev_b32_e32 v251, 2, v251
	s_waitcnt lgkmcnt(0)
	v_max_f32_e32 v250, v250, v250
	ds_bpermute_b32 v252, v251, v249
	v_max_f32_e32 v248, v248, v250
	ds_bpermute_b32 v250, v251, v248
	s_waitcnt lgkmcnt(1)
	v_max_f32_e32 v251, v252, v252
	v_max_f32_e32 v249, v249, v251
	s_waitcnt lgkmcnt(0)
	v_max_f32_e32 v250, v250, v250
	v_max_f32_e32 v248, v248, v250
	v_cmp_lt_f32_e32 vcc, s8, v249
	s_nop 1
	v_cndmask_b32_e32 v249, 0, v249, vcc
	v_cmp_lt_f32_e32 vcc, s8, v248
	v_sub_f32_e32 v148, v148, v249
	v_sub_f32_e32 v149, v149, v249
	v_cndmask_b32_e32 v252, 0, v248, vcc
	v_exp_f32_e64 v248, -v249
	v_exp_f32_e64 v250, -v252
	v_sub_f32_e32 v150, v150, v249
	v_sub_f32_e32 v151, v151, v249
	v_sub_f32_e32 v152, v152, v252
	v_pk_mul_f32 v[118:119], v[118:119], v[250:251] op_sel_hi:[1,0]
	v_pk_mul_f32 v[116:117], v[116:117], v[250:251] op_sel_hi:[1,0]
	v_pk_mul_f32 v[110:111], v[110:111], v[250:251] op_sel_hi:[1,0]
	v_pk_mul_f32 v[108:109], v[108:109], v[250:251] op_sel_hi:[1,0]
	v_pk_mul_f32 v[102:103], v[102:103], v[250:251] op_sel_hi:[1,0]
	v_pk_mul_f32 v[100:101], v[100:101], v[250:251] op_sel_hi:[1,0]
	v_pk_mul_f32 v[98:99], v[98:99], v[250:251] op_sel_hi:[1,0]
	v_pk_mul_f32 v[96:97], v[96:97], v[250:251] op_sel_hi:[1,0]
	v_mov_b32_e32 v251, v248
	v_sub_f32_e32 v153, v153, v252
	v_sub_f32_e32 v154, v154, v252
	v_sub_f32_e32 v155, v155, v252
	v_pk_mul_f32 v[122:123], v[122:123], v[248:249] op_sel_hi:[1,0]
	v_pk_mul_f32 v[120:121], v[120:121], v[248:249] op_sel_hi:[1,0]
	v_sub_f32_e32 v140, v140, v249
	v_sub_f32_e32 v141, v141, v249
	v_sub_f32_e32 v142, v142, v249
	v_sub_f32_e32 v143, v143, v249
	v_sub_f32_e32 v144, v144, v252
	v_sub_f32_e32 v145, v145, v252
	v_sub_f32_e32 v146, v146, v252
	v_sub_f32_e32 v147, v147, v252
	v_pk_mul_f32 v[114:115], v[114:115], v[248:249] op_sel_hi:[1,0]
	v_pk_mul_f32 v[112:113], v[112:113], v[248:249] op_sel_hi:[1,0]
	v_sub_f32_e32 v132, v132, v249
	v_sub_f32_e32 v133, v133, v249
	v_sub_f32_e32 v134, v134, v249
	v_sub_f32_e32 v135, v135, v249
	v_sub_f32_e32 v136, v136, v252
	v_sub_f32_e32 v137, v137, v252
	v_sub_f32_e32 v138, v138, v252
	v_sub_f32_e32 v139, v139, v252
	v_pk_mul_f32 v[106:107], v[106:107], v[248:249] op_sel_hi:[1,0]
	v_pk_mul_f32 v[104:105], v[104:105], v[248:249] op_sel_hi:[1,0]
	v_sub_f32_e32 v124, v124, v249
	v_sub_f32_e32 v125, v125, v249
	v_sub_f32_e32 v126, v126, v249
	v_sub_f32_e32 v127, v127, v249
	v_sub_f32_e32 v128, v128, v252
	v_sub_f32_e32 v129, v129, v252
	v_sub_f32_e32 v130, v130, v252
	v_sub_f32_e32 v131, v131, v252
	v_pk_mul_f32 v[94:95], v[94:95], v[248:249] op_sel_hi:[1,0]
	v_pk_mul_f32 v[92:93], v[92:93], v[248:249] op_sel_hi:[1,0]
	v_pk_mul_f32 v[184:185], v[184:185], v[250:251]
	v_sub_f32_e32 v47, v47, v249
	v_sub_f32_e32 v46, v46, v249
	v_sub_f32_e32 v45, v45, v249
	v_sub_f32_e32 v44, v44, v249
	v_sub_f32_e32 v51, v51, v252
	v_sub_f32_e32 v50, v50, v252
	v_sub_f32_e32 v49, v49, v252
	v_sub_f32_e32 v48, v48, v252
